# v087 + the down GEMM loop's LDS read addresses folded into offsets too (all six K-loops VALU-free)
# baseline (speedup 1.0000x reference)
.LBB0_1274:
	s_lshl_b64 s[40:41], s[16:17], 15
	s_lshl_b64 s[42:43], s[16:17], 7
	s_and_b64 s[16:17], s[38:39], exec
	s_cselect_b32 s10, s40, 0
	s_cselect_b32 s5, s41, 0
	s_add_u32 s16, s28, s10
	s_addc_u32 s17, s29, s5
	s_and_b64 s[28:29], s[38:39], exec
	s_cselect_b32 s10, s42, 0
	s_cselect_b32 s5, s43, 0
	s_add_u32 s28, s30, s10
	s_addc_u32 s29, s31, s5
	s_cmp_lt_i32 s54, 1
	s_cbranch_scc1 .LBB0_1277
	s_add_i32 s5, s54, -2
	s_add_u32 s44, s6, 0x100
	s_addc_u32 s45, s7, 0
	s_add_u32 s30, s8, 0xc000
	s_addc_u32 s31, s9, 0
	s_mov_b32 s38, 0
	v_add_u32_e32 v172, 0x10000, v210
.LBB0_1276:
	s_add_i32 vcc_lo, s38, 2
	s_add_u32 s10, s30, 0x4000
	s_addc_u32 s11, s31, 0
	s_cmp_eq_u32 s5, s38
	s_cselect_b32 s42, s16, s10
	s_cselect_b32 s43, s17, s11
	s_cselect_b32 s40, s28, s44
	s_cselect_b32 s41, s29, s45
	s_add_u32 s38, s42, 0x8000
	s_addc_u32 s39, s43, 0
	s_add_i32 s10, 0, 0x10000
	s_add_i32 vcc_hi, 0, 0x14000
	ds_read_b128 v[132:135], v172
	ds_read_b128 v[136:139], v172 offset:1024
	ds_read_b128 v[140:143], v172 offset:2048
	ds_read_b128 v[144:147], v172 offset:3072
	ds_read_b128 v[148:151], v172 offset:16384
	ds_read_b128 v[152:155], v172 offset:17408
	ds_read_b128 v[156:159], v172 offset:18432
	ds_read_b128 v[160:163], v172 offset:19456
	s_add_i32 m0, s62, 0xc000
	ds_read_b128 v[164:167], v212
	ds_read_b128 v[168:171], v212 offset:1024
	ds_read_b128 v[188:191], v212 offset:2048
	ds_read_b128 v[192:195], v212 offset:3072
	ds_read_b128 v[196:199], v212 offset:4096
	ds_read_b128 v[222:225], v212 offset:5120
	ds_read_b128 v[226:229], v212 offset:6144
	ds_read_b128 v[230:233], v212 offset:7168
	global_load_lds_dwordx4 v186, s[30:31]
	s_add_i32 m0, s62, 0xe000
	s_nop 0
	global_load_lds_dwordx4 v184, s[30:31]
	s_waitcnt vmcnt(8)
	s_waitcnt lgkmcnt(0)
	s_barrier
	s_setprio 1
	s_waitcnt lgkmcnt(0)
	v_mfma_f32_16x16x32_bf16 v[2:5], v[132:135], v[164:167], v[2:5]
	v_mfma_f32_16x16x32_bf16 v[6:9], v[140:143], v[164:167], v[6:9]
	v_mfma_f32_16x16x32_bf16 v[10:13], v[132:135], v[188:191], v[10:13]
	v_mfma_f32_16x16x32_bf16 v[14:17], v[140:143], v[188:191], v[14:17]
	v_mfma_f32_16x16x32_bf16 v[18:21], v[132:135], v[196:199], v[18:21]
	v_mfma_f32_16x16x32_bf16 v[22:25], v[140:143], v[196:199], v[22:25]
	v_mfma_f32_16x16x32_bf16 v[26:29], v[132:135], v[226:229], v[26:29]
	v_mfma_f32_16x16x32_bf16 v[30:33], v[140:143], v[226:229], v[30:33]
	v_mfma_f32_16x16x32_bf16 v[2:5], v[136:139], v[168:171], v[2:5]
	v_mfma_f32_16x16x32_bf16 v[6:9], v[144:147], v[168:171], v[6:9]
	v_mfma_f32_16x16x32_bf16 v[10:13], v[136:139], v[192:195], v[10:13]
	v_mfma_f32_16x16x32_bf16 v[14:17], v[144:147], v[192:195], v[14:17]
	v_mfma_f32_16x16x32_bf16 v[18:21], v[136:139], v[222:225], v[18:21]
	v_mfma_f32_16x16x32_bf16 v[22:25], v[144:147], v[222:225], v[22:25]
	v_mfma_f32_16x16x32_bf16 v[26:29], v[136:139], v[230:233], v[26:29]
	v_mfma_f32_16x16x32_bf16 v[30:33], v[144:147], v[230:233], v[30:33]
	s_setprio 0
	s_setprio 1
	v_mfma_f32_16x16x32_bf16 v[34:37], v[148:151], v[164:167], v[34:37]
	v_mfma_f32_16x16x32_bf16 v[38:41], v[156:159], v[164:167], v[38:41]
	v_mfma_f32_16x16x32_bf16 v[42:45], v[148:151], v[188:191], v[42:45]
	v_mfma_f32_16x16x32_bf16 v[46:49], v[156:159], v[188:191], v[46:49]
	v_mfma_f32_16x16x32_bf16 v[50:53], v[148:151], v[196:199], v[50:53]
	v_mfma_f32_16x16x32_bf16 v[54:57], v[156:159], v[196:199], v[54:57]
	v_mfma_f32_16x16x32_bf16 v[58:61], v[148:151], v[226:229], v[58:61]
	v_mfma_f32_16x16x32_bf16 v[62:65], v[156:159], v[226:229], v[62:65]
	v_mfma_f32_16x16x32_bf16 v[34:37], v[152:155], v[168:171], v[34:37]
	v_mfma_f32_16x16x32_bf16 v[38:41], v[160:163], v[168:171], v[38:41]
	v_mfma_f32_16x16x32_bf16 v[42:45], v[152:155], v[192:195], v[42:45]
	v_mfma_f32_16x16x32_bf16 v[46:49], v[160:163], v[192:195], v[46:49]
	v_mfma_f32_16x16x32_bf16 v[50:53], v[152:155], v[222:225], v[50:53]
	v_mfma_f32_16x16x32_bf16 v[54:57], v[160:163], v[222:225], v[54:57]
	v_mfma_f32_16x16x32_bf16 v[58:61], v[152:155], v[230:233], v[58:61]
	v_mfma_f32_16x16x32_bf16 v[62:65], v[160:163], v[230:233], v[62:65]
	s_setprio 0
	s_barrier
	s_add_i32 s10, s10, s61
	s_add_u32 s98, s40, s34
	s_addc_u32 s99, s41, s35
	s_mov_b32 m0, s10
	ds_read_b128 v[164:167], v212 offset:16384
	ds_read_b128 v[168:171], v212 offset:17408
	ds_read_b128 v[188:191], v212 offset:18432
	ds_read_b128 v[192:195], v212 offset:19456
	ds_read_b128 v[196:199], v212 offset:20480
	ds_read_b128 v[222:225], v212 offset:21504
	ds_read_b128 v[226:229], v212 offset:22528
	ds_read_b128 v[230:233], v212 offset:23552
	global_load_lds_dwordx4 v178, s[40:41]
	s_add_i32 m0, s10, 0x2000
	s_add_u32 s10, s40, 0x160000
	s_addc_u32 s11, s41, 0
	s_add_i32 vcc_hi, vcc_hi, s61
	global_load_lds_dwordx4 v182, s[40:41]
	s_mov_b32 m0, vcc_hi
	s_nop 0
	global_load_lds_dwordx4 v178, s[10:11]
	s_add_i32 m0, vcc_hi, 0x2000
	s_nop 0
	global_load_lds_dwordx4 v182, s[10:11]
	s_mov_b32 m0, s62
	s_nop 0
	global_load_lds_dwordx4 v176, s[42:43]
	s_mov_b32 m0, s63
	s_nop 0
	global_load_lds_dwordx4 v180, s[42:43]
	s_waitcnt vmcnt(8)
	s_waitcnt lgkmcnt(0)
	s_barrier
	s_setprio 1
	s_waitcnt lgkmcnt(0)
	v_mfma_f32_16x16x32_bf16 v[66:69], v[132:135], v[164:167], v[66:69]
	v_mfma_f32_16x16x32_bf16 v[70:73], v[140:143], v[164:167], v[70:73]
	v_mfma_f32_16x16x32_bf16 v[74:77], v[132:135], v[188:191], v[74:77]
	v_mfma_f32_16x16x32_bf16 v[78:81], v[140:143], v[188:191], v[78:81]
	v_mfma_f32_16x16x32_bf16 v[82:85], v[132:135], v[196:199], v[82:85]
	v_mfma_f32_16x16x32_bf16 v[86:89], v[140:143], v[196:199], v[86:89]
	v_mfma_f32_16x16x32_bf16 v[90:93], v[132:135], v[226:229], v[90:93]
	v_mfma_f32_16x16x32_bf16 v[94:97], v[140:143], v[226:229], v[94:97]
	v_mfma_f32_16x16x32_bf16 v[66:69], v[136:139], v[168:171], v[66:69]
	v_mfma_f32_16x16x32_bf16 v[70:73], v[144:147], v[168:171], v[70:73]
	v_mfma_f32_16x16x32_bf16 v[74:77], v[136:139], v[192:195], v[74:77]
	v_mfma_f32_16x16x32_bf16 v[78:81], v[144:147], v[192:195], v[78:81]
	v_mfma_f32_16x16x32_bf16 v[82:85], v[136:139], v[222:225], v[82:85]
	v_mfma_f32_16x16x32_bf16 v[86:89], v[144:147], v[222:225], v[86:89]
	v_mfma_f32_16x16x32_bf16 v[90:93], v[136:139], v[230:233], v[90:93]
	v_mfma_f32_16x16x32_bf16 v[94:97], v[144:147], v[230:233], v[94:97]
	s_setprio 0
	s_setprio 1
	v_mfma_f32_16x16x32_bf16 v[98:101], v[148:151], v[164:167], v[98:101]
	v_mfma_f32_16x16x32_bf16 v[102:105], v[156:159], v[164:167], v[102:105]
	v_mfma_f32_16x16x32_bf16 v[106:109], v[148:151], v[188:191], v[106:109]
	v_mfma_f32_16x16x32_bf16 v[110:113], v[156:159], v[188:191], v[110:113]
	v_mfma_f32_16x16x32_bf16 v[114:117], v[148:151], v[196:199], v[114:117]
	v_mfma_f32_16x16x32_bf16 v[118:121], v[156:159], v[196:199], v[118:121]
	v_mfma_f32_16x16x32_bf16 v[122:125], v[148:151], v[226:229], v[122:125]
	v_mfma_f32_16x16x32_bf16 v[126:129], v[156:159], v[226:229], v[126:129]
	v_mfma_f32_16x16x32_bf16 v[98:101], v[152:155], v[168:171], v[98:101]
	v_mfma_f32_16x16x32_bf16 v[102:105], v[160:163], v[168:171], v[102:105]
	v_mfma_f32_16x16x32_bf16 v[106:109], v[152:155], v[192:195], v[106:109]
	v_mfma_f32_16x16x32_bf16 v[110:113], v[160:163], v[192:195], v[110:113]
	v_mfma_f32_16x16x32_bf16 v[114:117], v[152:155], v[222:225], v[114:117]
	v_mfma_f32_16x16x32_bf16 v[118:121], v[160:163], v[222:225], v[118:121]
	v_mfma_f32_16x16x32_bf16 v[122:125], v[152:155], v[230:233], v[122:125]
	v_mfma_f32_16x16x32_bf16 v[126:129], v[160:163], v[230:233], v[126:129]
	s_setprio 0
	s_barrier
	s_add_i32 vcc_hi, 0, 0x18000
	s_add_i32 s81, 0, 0x1c000
	ds_read_b128 v[132:135], v172 offset:32768
	ds_read_b128 v[136:139], v172 offset:33792
	ds_read_b128 v[140:143], v172 offset:34816
	ds_read_b128 v[144:147], v172 offset:35840
	ds_read_b128 v[148:151], v172 offset:49152
	ds_read_b128 v[152:155], v172 offset:50176
	ds_read_b128 v[156:159], v172 offset:51200
	ds_read_b128 v[160:163], v172 offset:52224
	s_add_u32 s10, s42, 0x4000
	s_addc_u32 s11, s43, 0
	s_mov_b32 m0, s68
	ds_read_b128 v[164:167], v212 offset:32768
	ds_read_b128 v[168:171], v212 offset:33792
	ds_read_b128 v[188:191], v212 offset:34816
	ds_read_b128 v[192:195], v212 offset:35840
	ds_read_b128 v[196:199], v212 offset:36864
	ds_read_b128 v[222:225], v212 offset:37888
	ds_read_b128 v[226:229], v212 offset:38912
	ds_read_b128 v[230:233], v212 offset:39936
	global_load_lds_dwordx4 v176, s[10:11]
	s_mov_b32 m0, s69
	s_nop 0
	global_load_lds_dwordx4 v180, s[10:11]
	s_waitcnt vmcnt(8)
	s_waitcnt lgkmcnt(0)
	s_barrier
	s_setprio 1
	s_waitcnt lgkmcnt(0)
	v_mfma_f32_16x16x32_bf16 v[2:5], v[132:135], v[164:167], v[2:5]
	v_mfma_f32_16x16x32_bf16 v[6:9], v[140:143], v[164:167], v[6:9]
	v_mfma_f32_16x16x32_bf16 v[10:13], v[132:135], v[188:191], v[10:13]
	v_mfma_f32_16x16x32_bf16 v[14:17], v[140:143], v[188:191], v[14:17]
	v_mfma_f32_16x16x32_bf16 v[18:21], v[132:135], v[196:199], v[18:21]
	v_mfma_f32_16x16x32_bf16 v[22:25], v[140:143], v[196:199], v[22:25]
	v_mfma_f32_16x16x32_bf16 v[26:29], v[132:135], v[226:229], v[26:29]
	v_mfma_f32_16x16x32_bf16 v[30:33], v[140:143], v[226:229], v[30:33]
	v_mfma_f32_16x16x32_bf16 v[2:5], v[136:139], v[168:171], v[2:5]
	v_mfma_f32_16x16x32_bf16 v[6:9], v[144:147], v[168:171], v[6:9]
	v_mfma_f32_16x16x32_bf16 v[10:13], v[136:139], v[192:195], v[10:13]
	v_mfma_f32_16x16x32_bf16 v[14:17], v[144:147], v[192:195], v[14:17]
	v_mfma_f32_16x16x32_bf16 v[18:21], v[136:139], v[222:225], v[18:21]
	v_mfma_f32_16x16x32_bf16 v[22:25], v[144:147], v[222:225], v[22:25]
	v_mfma_f32_16x16x32_bf16 v[26:29], v[136:139], v[230:233], v[26:29]
	v_mfma_f32_16x16x32_bf16 v[30:33], v[144:147], v[230:233], v[30:33]
	s_setprio 0
	s_setprio 1
	v_mfma_f32_16x16x32_bf16 v[34:37], v[148:151], v[164:167], v[34:37]
	v_mfma_f32_16x16x32_bf16 v[38:41], v[156:159], v[164:167], v[38:41]
	v_mfma_f32_16x16x32_bf16 v[42:45], v[148:151], v[188:191], v[42:45]
	v_mfma_f32_16x16x32_bf16 v[46:49], v[156:159], v[188:191], v[46:49]
	v_mfma_f32_16x16x32_bf16 v[50:53], v[148:151], v[196:199], v[50:53]
	v_mfma_f32_16x16x32_bf16 v[54:57], v[156:159], v[196:199], v[54:57]
	v_mfma_f32_16x16x32_bf16 v[58:61], v[148:151], v[226:229], v[58:61]
	v_mfma_f32_16x16x32_bf16 v[62:65], v[156:159], v[226:229], v[62:65]
	v_mfma_f32_16x16x32_bf16 v[34:37], v[152:155], v[168:171], v[34:37]
	v_mfma_f32_16x16x32_bf16 v[38:41], v[160:163], v[168:171], v[38:41]
	v_mfma_f32_16x16x32_bf16 v[42:45], v[152:155], v[192:195], v[42:45]
	v_mfma_f32_16x16x32_bf16 v[46:49], v[160:163], v[192:195], v[46:49]
	v_mfma_f32_16x16x32_bf16 v[50:53], v[152:155], v[222:225], v[50:53]
	v_mfma_f32_16x16x32_bf16 v[54:57], v[160:163], v[222:225], v[54:57]
	v_mfma_f32_16x16x32_bf16 v[58:61], v[152:155], v[230:233], v[58:61]
	v_mfma_f32_16x16x32_bf16 v[62:65], v[160:163], v[230:233], v[62:65]
	s_setprio 0
	s_barrier
	s_add_i32 s10, vcc_hi, s61
	s_mov_b32 m0, s10
	ds_read_b128 v[164:167], v212 offset:49152
	ds_read_b128 v[168:171], v212 offset:50176
	ds_read_b128 v[188:191], v212 offset:51200
	ds_read_b128 v[192:195], v212 offset:52224
	ds_read_b128 v[196:199], v212 offset:53248
	ds_read_b128 v[222:225], v212 offset:54272
	ds_read_b128 v[226:229], v212 offset:55296
	ds_read_b128 v[230:233], v212 offset:56320
	global_load_lds_dwordx4 v178, s[98:99]
	s_add_i32 m0, s10, 0x2000
	s_add_u32 s10, s40, 0x160080
	s_addc_u32 s11, s41, 0
	s_add_i32 s40, s81, s61
	global_load_lds_dwordx4 v182, s[98:99]
	s_mov_b32 m0, s40
	s_nop 0
	global_load_lds_dwordx4 v178, s[10:11]
	s_add_i32 m0, s40, 0x2000
	s_nop 0
	global_load_lds_dwordx4 v182, s[10:11]
	s_mov_b32 m0, s75
	s_nop 0
	global_load_lds_dwordx4 v176, s[38:39]
	s_mov_b32 m0, s76
	s_nop 0
	global_load_lds_dwordx4 v180, s[38:39]
	s_waitcnt vmcnt(8)
	s_waitcnt lgkmcnt(0)
	s_barrier
	s_setprio 1
	s_waitcnt lgkmcnt(0)
	v_mfma_f32_16x16x32_bf16 v[66:69], v[132:135], v[164:167], v[66:69]
	v_mfma_f32_16x16x32_bf16 v[70:73], v[140:143], v[164:167], v[70:73]
	v_mfma_f32_16x16x32_bf16 v[74:77], v[132:135], v[188:191], v[74:77]
	v_mfma_f32_16x16x32_bf16 v[78:81], v[140:143], v[188:191], v[78:81]
	v_mfma_f32_16x16x32_bf16 v[82:85], v[132:135], v[196:199], v[82:85]
	v_mfma_f32_16x16x32_bf16 v[86:89], v[140:143], v[196:199], v[86:89]
	v_mfma_f32_16x16x32_bf16 v[90:93], v[132:135], v[226:229], v[90:93]
	v_mfma_f32_16x16x32_bf16 v[94:97], v[140:143], v[226:229], v[94:97]
	v_mfma_f32_16x16x32_bf16 v[66:69], v[136:139], v[168:171], v[66:69]
	v_mfma_f32_16x16x32_bf16 v[70:73], v[144:147], v[168:171], v[70:73]
	v_mfma_f32_16x16x32_bf16 v[74:77], v[136:139], v[192:195], v[74:77]
	v_mfma_f32_16x16x32_bf16 v[78:81], v[144:147], v[192:195], v[78:81]
	v_mfma_f32_16x16x32_bf16 v[82:85], v[136:139], v[222:225], v[82:85]
	v_mfma_f32_16x16x32_bf16 v[86:89], v[144:147], v[222:225], v[86:89]
	v_mfma_f32_16x16x32_bf16 v[90:93], v[136:139], v[230:233], v[90:93]
	v_mfma_f32_16x16x32_bf16 v[94:97], v[144:147], v[230:233], v[94:97]
	s_setprio 0
	s_setprio 1
	v_mfma_f32_16x16x32_bf16 v[98:101], v[148:151], v[164:167], v[98:101]
	v_mfma_f32_16x16x32_bf16 v[102:105], v[156:159], v[164:167], v[102:105]
	v_mfma_f32_16x16x32_bf16 v[106:109], v[148:151], v[188:191], v[106:109]
	v_mfma_f32_16x16x32_bf16 v[110:113], v[156:159], v[188:191], v[110:113]
	v_mfma_f32_16x16x32_bf16 v[114:117], v[148:151], v[196:199], v[114:117]
	v_mfma_f32_16x16x32_bf16 v[118:121], v[156:159], v[196:199], v[118:121]
	v_mfma_f32_16x16x32_bf16 v[122:125], v[148:151], v[226:229], v[122:125]
	v_mfma_f32_16x16x32_bf16 v[126:129], v[156:159], v[226:229], v[126:129]
	v_mfma_f32_16x16x32_bf16 v[98:101], v[152:155], v[168:171], v[98:101]
	v_mfma_f32_16x16x32_bf16 v[102:105], v[160:163], v[168:171], v[102:105]
	v_mfma_f32_16x16x32_bf16 v[106:109], v[152:155], v[192:195], v[106:109]
	v_mfma_f32_16x16x32_bf16 v[110:113], v[160:163], v[192:195], v[110:113]
	v_mfma_f32_16x16x32_bf16 v[114:117], v[152:155], v[222:225], v[114:117]
	v_mfma_f32_16x16x32_bf16 v[118:121], v[160:163], v[222:225], v[118:121]
	v_mfma_f32_16x16x32_bf16 v[122:125], v[152:155], v[230:233], v[122:125]
	v_mfma_f32_16x16x32_bf16 v[126:129], v[160:163], v[230:233], v[126:129]
	s_setprio 0
	s_barrier
	s_add_u32 s44, s44, 0x100
	s_addc_u32 s45, s45, 0
	s_add_u32 s30, s30, 0x10000
	s_addc_u32 s31, s31, 0
	s_cmp_ge_i32 vcc_lo, s54
	s_mov_b32 s38, vcc_lo
	s_cbranch_scc0 .LBB0_1276
